# same as previous best; GEMM stream pointer moved from s54/s55 to free s86/s87 (register hygiene)
# speedup vs baseline: 1.0017x; 1.0017x over previous
; DEVI void phase_gemm_big(const Params& p, int mode, bf16_t* smem) {
;     ...
;   for (int L = li; L < per_xcd; L += nli) {
;     const int mg = L / (8 * NT), rem = L % (8 * NT), nt = rem >> 3, mt = xcd * 40 + mg * 8 + (rem & 7), m0 = mt * 256, n0 = nt * 128;
;     const int Ln = L + nli < per_xcd ? L + nli : L;
;     const int mgn = Ln / (8 * NT), remn = Ln % (8 * NT), m0n = (xcd * 40 + mgn * 8 + (remn & 7)) * 256, n0n = (remn >> 3) * 128;
;     f32x4 acc[8][4];
; #pragma unroll
;     for (int i = 0; i < 8; ++i)
; #pragma unroll
;       for (int j = 0; j < 4; ++j) acc[i][j] = (f32x4){0.f, 0.f, 0.f, 0.f};
;     gemm_kloop2(Abase + (size_t)m0 * 1024, 1024, Bbase + (size_t)n0 * 1024, 1024,
;                 Abase + (size_t)m0n * 1024, 1024, Bbase + (size_t)n0n * 1024, 1024, first, smem, acc);
.Lg1_go:
	s_add_u32 s86, s42, 0x80
	s_addc_u32 s87, s43, 0
	s_add_u32 s56, s44, 0x80
	s_addc_u32 s57, s45, 0
	s_add_i32 s35, s41, s83
	s_cmpk_gt_i32 s35, 0x54f
	s_cselect_b64 s[38:39], -1, 0
	s_cmpk_lt_i32 s35, 0x550
	s_cselect_b32 s2, s35, s41
	s_mul_hi_i32 s3, s2, 0x78787879
	s_lshr_b32 s37, s3, 31
	s_ashr_i32 s3, s3, 7
	s_add_i32 s3, s3, s37
	s_mul_i32 s37, s3, 0x110
	s_sub_i32 s2, s2, s37
	s_lshl_b32 s3, s3, 3
	s_add_i32 s3, s3, s40
	s_and_b32 s37, s2, 7
	s_or_b32 s3, s3, s37
	s_lshl_b32 s37, s2, 4
	s_lshl_b32 s2, s3, 8
	s_ashr_i32 s3, s2, 31
	s_and_b32 s42, s37, 0xffffff80
	s_lshl_b64 s[2:3], s[2:3], 11
	s_add_u32 s2, s20, s2
	s_addc_u32 s3, s21, s3
	s_ashr_i32 s43, s42, 31
	s_lshl_b64 s[42:43], s[42:43], 11
	s_add_u32 s42, s0, s42
	s_addc_u32 s43, s1, s43
	s_mov_b64 s[58:59], s[2:3]
	s_mov_b64 s[60:61], s[42:43]
	s_mov_b32 s65, 0
	v_mov_b32_e32 v2, 0
	v_mov_b32_e32 v3, v2
	v_mov_b32_e32 v4, v2
	v_mov_b32_e32 v5, v2
	v_mov_b32_e32 v6, v2
	v_mov_b32_e32 v7, v2
	v_mov_b32_e32 v8, v2
	v_mov_b32_e32 v9, v2
	v_mov_b32_e32 v10, v2
	v_mov_b32_e32 v11, v2
	v_mov_b32_e32 v12, v2
	v_mov_b32_e32 v13, v2
	v_mov_b32_e32 v14, v2
	v_mov_b32_e32 v15, v2
	v_mov_b32_e32 v16, v2
	v_mov_b32_e32 v17, v2
	v_mov_b32_e32 v18, v2
	v_mov_b32_e32 v19, v2
	v_mov_b32_e32 v20, v2
	v_mov_b32_e32 v21, v2
	v_mov_b32_e32 v22, v2
	v_mov_b32_e32 v23, v2
	v_mov_b32_e32 v24, v2
	v_mov_b32_e32 v25, v2
	v_mov_b32_e32 v26, v2
	v_mov_b32_e32 v27, v2
	v_mov_b32_e32 v28, v2
	v_mov_b32_e32 v29, v2
	v_mov_b32_e32 v30, v2
	v_mov_b32_e32 v31, v2
	v_mov_b32_e32 v32, v2
	v_mov_b32_e32 v33, v2
	v_mov_b32_e32 v34, v2
	v_mov_b32_e32 v35, v2
	v_mov_b32_e32 v36, v2
	v_mov_b32_e32 v37, v2
	v_mov_b32_e32 v38, v2
	v_mov_b32_e32 v39, v2
	v_mov_b32_e32 v40, v2
	v_mov_b32_e32 v41, v2
	v_mov_b32_e32 v42, v2
	v_mov_b32_e32 v43, v2
	v_mov_b32_e32 v44, v2
	v_mov_b32_e32 v45, v2
	v_mov_b32_e32 v46, v2
	v_mov_b32_e32 v47, v2
	v_mov_b32_e32 v48, v2
	v_mov_b32_e32 v49, v2
	v_mov_b32_e32 v50, v2
	v_mov_b32_e32 v51, v2
	v_mov_b32_e32 v52, v2
	v_mov_b32_e32 v53, v2
	v_mov_b32_e32 v54, v2
	v_mov_b32_e32 v55, v2
	v_mov_b32_e32 v56, v2
	v_mov_b32_e32 v57, v2
	v_mov_b32_e32 v58, v2
	v_mov_b32_e32 v59, v2
	v_mov_b32_e32 v60, v2
	v_mov_b32_e32 v61, v2
	v_mov_b32_e32 v62, v2
	v_mov_b32_e32 v63, v2
	v_mov_b32_e32 v64, v2
	v_mov_b32_e32 v65, v2
	v_mov_b32_e32 v66, v2
	v_mov_b32_e32 v67, v2
	v_mov_b32_e32 v68, v2
	v_mov_b32_e32 v69, v2
	v_mov_b32_e32 v70, v2
	v_mov_b32_e32 v71, v2
	v_mov_b32_e32 v72, v2
	v_mov_b32_e32 v73, v2
	v_mov_b32_e32 v74, v2
	v_mov_b32_e32 v75, v2
	v_mov_b32_e32 v76, v2
	v_mov_b32_e32 v77, v2
	v_mov_b32_e32 v78, v2
	v_mov_b32_e32 v79, v2
	v_mov_b32_e32 v80, v2
	v_mov_b32_e32 v81, v2
	v_mov_b32_e32 v82, v2
	v_mov_b32_e32 v83, v2
	v_mov_b32_e32 v84, v2
	v_mov_b32_e32 v85, v2
	v_mov_b32_e32 v86, v2
	v_mov_b32_e32 v87, v2
	v_mov_b32_e32 v88, v2
	v_mov_b32_e32 v89, v2
	v_mov_b32_e32 v90, v2
	v_mov_b32_e32 v91, v2
	v_mov_b32_e32 v92, v2
	v_mov_b32_e32 v93, v2
	v_mov_b32_e32 v94, v2
	v_mov_b32_e32 v95, v2
	v_mov_b32_e32 v96, v2
	v_mov_b32_e32 v97, v2
	v_mov_b32_e32 v98, v2
	v_mov_b32_e32 v99, v2
	v_mov_b32_e32 v100, v2
	v_mov_b32_e32 v101, v2
	v_mov_b32_e32 v102, v2
	v_mov_b32_e32 v103, v2
	v_mov_b32_e32 v104, v2
	v_mov_b32_e32 v105, v2
	v_mov_b32_e32 v106, v2
	v_mov_b32_e32 v107, v2
	v_mov_b32_e32 v108, v2
	v_mov_b32_e32 v109, v2
	v_mov_b32_e32 v110, v2
	v_mov_b32_e32 v111, v2
	v_mov_b32_e32 v112, v2
	v_mov_b32_e32 v113, v2
	v_mov_b32_e32 v114, v2
	v_mov_b32_e32 v115, v2
	v_mov_b32_e32 v116, v2
	v_mov_b32_e32 v117, v2
	v_mov_b32_e32 v118, v2
	v_mov_b32_e32 v119, v2
	v_mov_b32_e32 v120, v2
	v_mov_b32_e32 v121, v2
	v_mov_b32_e32 v122, v2
	v_mov_b32_e32 v123, v2
	v_mov_b32_e32 v124, v2
	v_mov_b32_e32 v125, v2
	v_mov_b32_e32 v126, v2
	v_mov_b32_e32 v127, v2
	v_mov_b32_e32 v128, v2
	v_mov_b32_e32 v129, v2

.Lg1_wd:
	s_barrier
	v_add_u32_e32 v130, s50, v212
	v_add_u32_e32 v131, s50, v213
	s_xor_b32 s16, s50, 0x8000
	s_add_u32 m0, s16, s52
	ds_read_b128 v[236:239], v192
	ds_read_b128 v[240:243], v192 offset:2048
	ds_read_b128 v[244:247], v192 offset:4096
	ds_read_b128 v[146:149], v192 offset:6144
	ds_read_b128 v[150:153], v193
	ds_read_b128 v[154:157], v193 offset:2048
	ds_read_b128 v[158:161], v193 offset:4096
	ds_read_b128 v[162:165], v193 offset:6144
	ds_read_b128 v[168:171], v130
	ds_read_b128 v[172:175], v130 offset:2048
	ds_read_b128 v[176:179], v130 offset:4096
	ds_read_b128 v[180:183], v130 offset:6144
	ds_read_b128 v[184:187], v130 offset:8192
	ds_read_b128 v[188:191], v130 offset:10240
	ds_read_b128 v[228:231], v130 offset:12288
	global_load_lds_dwordx4 v200, s[86:87]
	global_load_lds_dwordx4 v201, s[86:87] offset:1024
	global_load_lds_dwordx4 v202, s[86:87] offset:2048
	global_load_lds_dwordx4 v203, s[86:87] offset:3072
	s_add_u32 m0, m0, 0x1000
	s_nop 0
	global_load_lds_dwordx4 v204, s[86:87]
	global_load_lds_dwordx4 v205, s[86:87] offset:1024
	global_load_lds_dwordx4 v206, s[86:87] offset:2048
	global_load_lds_dwordx4 v207, s[86:87] offset:3072
	s_waitcnt lgkmcnt(7)
	s_barrier
; DEVI void lds_barrier() { asm volatile("s_waitcnt lgkmcnt(0)\n\ts_barrier" ::: "memory"); }
; #define SSTORE2(P, buf_) do { \
;     *(uint4*)(wA + (buf_) * 256 * GS2) = P##a0; *(uint4*)(wA + (buf_) * 256 * GS2 + 64 * GS2) = P##a1; \
;     *(uint4*)(wA + (buf_) * 256 * GS2 + 128 * GS2) = P##a2; *(uint4*)(wA + (buf_) * 256 * GS2 + 192 * GS2) = P##a3; \
;     *(uint4*)(wB + (buf_) * 128 * GS2) = P##b0; *(uint4*)(wB + (buf_) * 128 * GS2 + 64 * GS2) = P##b1; } while (0)
; DEVI void gemm_kloop2(const bf16_t* __restrict__ A, size_t lda, const bf16_t* __restrict__ Bt, size_t ldb,
;                       const bf16_t* __restrict__ nA, size_t nlda, const bf16_t* __restrict__ nBt, size_t nldb,
;                       bool first, bf16_t* smem, f32x4 (&acc)[8][4]) {
;     ...
; #pragma unroll 1
;   for (int kt = 0; kt < nk - 2; kt += 2) {
;     COMPUTE2(0, GLOAD2(x, gA, gB, lda, ldb, kt + 1));
;     SSTORE2(x, 1);
;     lds_barrier();
;     COMPUTE2(1, GLOAD2(x, gA, gB, lda, ldb, kt + 2));
;     SSTORE2(x, 0);
;     lds_barrier();
;   }
	s_mov_b32 m0, s53
	s_nop 0
	global_load_lds_dwordx4 v208, s[56:57]
	global_load_lds_dwordx4 v209, s[56:57] offset:1024
	global_load_lds_dwordx4 v210, s[56:57] offset:2048
	global_load_lds_dwordx4 v211, s[56:57] offset:3072
	ds_read_b128 v[232:235], v130 offset:14336
	s_setprio 1
	s_waitcnt lgkmcnt(7)
	v_mfma_f32_16x16x32_bf16 v[114:117], v[236:239], v[168:171], v[114:117]
	v_mfma_f32_16x16x32_bf16 v[102:105], v[240:243], v[168:171], v[102:105]
	v_mfma_f32_16x16x32_bf16 v[94:97], v[244:247], v[168:171], v[94:97]
	v_mfma_f32_16x16x32_bf16 v[86:89], v[146:149], v[168:171], v[86:89]
	s_waitcnt lgkmcnt(6)
	v_mfma_f32_16x16x32_bf16 v[126:129], v[236:239], v[172:175], v[126:129]
	v_mfma_f32_16x16x32_bf16 v[122:125], v[240:243], v[172:175], v[122:125]
	ds_read_b128 v[168:171], v131
	v_mfma_f32_16x16x32_bf16 v[118:121], v[244:247], v[172:175], v[118:121]
	v_mfma_f32_16x16x32_bf16 v[110:113], v[146:149], v[172:175], v[110:113]
	s_waitcnt lgkmcnt(6)
	v_mfma_f32_16x16x32_bf16 v[106:109], v[236:239], v[176:179], v[106:109]
	v_mfma_f32_16x16x32_bf16 v[98:101], v[240:243], v[176:179], v[98:101]
	ds_read_b128 v[172:175], v131 offset:2048
	v_mfma_f32_16x16x32_bf16 v[90:93], v[244:247], v[176:179], v[90:93]
	v_mfma_f32_16x16x32_bf16 v[82:85], v[146:149], v[176:179], v[82:85]
	s_waitcnt lgkmcnt(6)
	v_mfma_f32_16x16x32_bf16 v[78:81], v[236:239], v[180:183], v[78:81]
	v_mfma_f32_16x16x32_bf16 v[74:77], v[240:243], v[180:183], v[74:77]
	ds_read_b128 v[176:179], v131 offset:4096
	v_mfma_f32_16x16x32_bf16 v[70:73], v[244:247], v[180:183], v[70:73]
	v_mfma_f32_16x16x32_bf16 v[66:69], v[146:149], v[180:183], v[66:69]
	s_waitcnt lgkmcnt(6)
	v_mfma_f32_16x16x32_bf16 v[62:65], v[236:239], v[184:187], v[62:65]
	v_mfma_f32_16x16x32_bf16 v[58:61], v[240:243], v[184:187], v[58:61]
	ds_read_b128 v[180:183], v131 offset:6144
	v_mfma_f32_16x16x32_bf16 v[54:57], v[244:247], v[184:187], v[54:57]
	v_mfma_f32_16x16x32_bf16 v[50:53], v[146:149], v[184:187], v[50:53]
	s_waitcnt lgkmcnt(6)
	v_mfma_f32_16x16x32_bf16 v[46:49], v[236:239], v[188:191], v[46:49]
	v_mfma_f32_16x16x32_bf16 v[42:45], v[240:243], v[188:191], v[42:45]
	ds_read_b128 v[184:187], v131 offset:8192
	v_mfma_f32_16x16x32_bf16 v[38:41], v[244:247], v[188:191], v[38:41]
	v_mfma_f32_16x16x32_bf16 v[34:37], v[146:149], v[188:191], v[34:37]
	s_waitcnt lgkmcnt(6)
	v_mfma_f32_16x16x32_bf16 v[30:33], v[236:239], v[228:231], v[30:33]
	v_mfma_f32_16x16x32_bf16 v[26:29], v[240:243], v[228:231], v[26:29]
	ds_read_b128 v[188:191], v131 offset:10240
	v_mfma_f32_16x16x32_bf16 v[22:25], v[244:247], v[228:231], v[22:25]
	v_mfma_f32_16x16x32_bf16 v[18:21], v[146:149], v[228:231], v[18:21]
	s_waitcnt lgkmcnt(6)
	v_mfma_f32_16x16x32_bf16 v[14:17], v[236:239], v[232:235], v[14:17]
	v_mfma_f32_16x16x32_bf16 v[10:13], v[240:243], v[232:235], v[10:13]
	ds_read_b128 v[228:231], v131 offset:12288
	v_mfma_f32_16x16x32_bf16 v[6:9], v[244:247], v[232:235], v[6:9]
	v_mfma_f32_16x16x32_bf16 v[2:5], v[146:149], v[232:235], v[2:5]
	s_waitcnt lgkmcnt(6)
	v_mfma_f32_16x16x32_bf16 v[114:117], v[150:153], v[168:171], v[114:117]
	v_mfma_f32_16x16x32_bf16 v[102:105], v[154:157], v[168:171], v[102:105]
	ds_read_b128 v[232:235], v131 offset:14336
	v_mfma_f32_16x16x32_bf16 v[94:97], v[158:161], v[168:171], v[94:97]
	v_mfma_f32_16x16x32_bf16 v[86:89], v[162:165], v[168:171], v[86:89]
	s_add_u32 s86, s86, 0x80
	s_waitcnt lgkmcnt(6)
	v_mfma_f32_16x16x32_bf16 v[126:129], v[150:153], v[172:175], v[126:129]
	v_mfma_f32_16x16x32_bf16 v[122:125], v[154:157], v[172:175], v[122:125]
	v_mfma_f32_16x16x32_bf16 v[118:121], v[158:161], v[172:175], v[118:121]
	v_mfma_f32_16x16x32_bf16 v[110:113], v[162:165], v[172:175], v[110:113]
	s_addc_u32 s87, s87, 0
	s_waitcnt lgkmcnt(5)
	v_mfma_f32_16x16x32_bf16 v[106:109], v[150:153], v[176:179], v[106:109]
	v_mfma_f32_16x16x32_bf16 v[98:101], v[154:157], v[176:179], v[98:101]
	v_mfma_f32_16x16x32_bf16 v[90:93], v[158:161], v[176:179], v[90:93]
	v_mfma_f32_16x16x32_bf16 v[82:85], v[162:165], v[176:179], v[82:85]
	s_add_u32 s56, s56, 0x80
	s_waitcnt lgkmcnt(4)
	v_mfma_f32_16x16x32_bf16 v[78:81], v[150:153], v[180:183], v[78:81]
	v_mfma_f32_16x16x32_bf16 v[74:77], v[154:157], v[180:183], v[74:77]
	v_mfma_f32_16x16x32_bf16 v[70:73], v[158:161], v[180:183], v[70:73]
	v_mfma_f32_16x16x32_bf16 v[66:69], v[162:165], v[180:183], v[66:69]
	s_addc_u32 s57, s57, 0
	s_waitcnt lgkmcnt(3)
	v_mfma_f32_16x16x32_bf16 v[62:65], v[150:153], v[184:187], v[62:65]
	v_mfma_f32_16x16x32_bf16 v[58:61], v[154:157], v[184:187], v[58:61]
	v_mfma_f32_16x16x32_bf16 v[54:57], v[158:161], v[184:187], v[54:57]
	v_mfma_f32_16x16x32_bf16 v[50:53], v[162:165], v[184:187], v[50:53]
	s_xor_b32 s50, s50, 0x8000
	s_waitcnt lgkmcnt(2)
	v_mfma_f32_16x16x32_bf16 v[46:49], v[150:153], v[188:191], v[46:49]
	v_mfma_f32_16x16x32_bf16 v[42:45], v[154:157], v[188:191], v[42:45]
	v_mfma_f32_16x16x32_bf16 v[38:41], v[158:161], v[188:191], v[38:41]
	v_mfma_f32_16x16x32_bf16 v[34:37], v[162:165], v[188:191], v[34:37]
	s_add_u32 s65, s65, 1
	s_waitcnt lgkmcnt(1)
	v_mfma_f32_16x16x32_bf16 v[30:33], v[150:153], v[228:231], v[30:33]
	v_mfma_f32_16x16x32_bf16 v[26:29], v[154:157], v[228:231], v[26:29]
	v_mfma_f32_16x16x32_bf16 v[22:25], v[158:161], v[228:231], v[22:25]
	v_mfma_f32_16x16x32_bf16 v[18:21], v[162:165], v[228:231], v[18:21]
	s_cmp_eq_u32 s65, 15
	s_waitcnt lgkmcnt(0)
	v_mfma_f32_16x16x32_bf16 v[14:17], v[150:153], v[232:235], v[14:17]
	v_mfma_f32_16x16x32_bf16 v[10:13], v[154:157], v[232:235], v[10:13]
	v_mfma_f32_16x16x32_bf16 v[6:9], v[158:161], v[232:235], v[6:9]
	v_mfma_f32_16x16x32_bf16 v[2:5], v[162:165], v[232:235], v[2:5]
	s_cselect_b64 s[86:87], s[58:59], s[86:87]
	s_cselect_b64 s[56:57], s[60:61], s[56:57]
	s_setprio 0
	s_cmp_lt_u32 s65, 16
	s_cbranch_scc1 .Lg1_loop
	s_nop 7
	s_nop 3
	v_add_u32_e32 v130, s36, v142
	s_cmpk_gt_i32 s34, 0x10ff
	v_ashrrev_i32_e32 v131, 31, v130
	s_mov_b64 s[2:3], -1
	s_cbranch_scc1 .LBB0_207
	s_andn2_b64 vcc, exec, s[2:3]
	s_cbranch_vccnz .LBB0_200
	s_branch .LBB0_208

; DEVI void phase_gemm_big(const Params& p, int mode, bf16_t* smem) {
;     ...
;   for (int L = li; L < per_xcd; L += nli) {
;     const int mg = L / (8 * NT), rem = L % (8 * NT), nt = rem >> 3, mt = xcd * 40 + mg * 8 + (rem & 7), m0 = mt * 256, n0 = nt * 128;
;     const int Ln = L + nli < per_xcd ? L + nli : L;
;     const int mgn = Ln / (8 * NT), remn = Ln % (8 * NT), m0n = (xcd * 40 + mgn * 8 + (remn & 7)) * 256, n0n = (remn >> 3) * 128;
;     f32x4 acc[8][4];
; #pragma unroll
;     for (int i = 0; i < 8; ++i)
; #pragma unroll
;       for (int j = 0; j < 4; ++j) acc[i][j] = (f32x4){0.f, 0.f, 0.f, 0.f};
;     gemm_kloop2(Abase + (size_t)m0 * 1024, 1024, Bbase + (size_t)n0 * 1024, 1024,
;                 Abase + (size_t)m0n * 1024, 1024, Bbase + (size_t)n0n * 1024, 1024, first, smem, acc);
.Lg2_go:
	s_add_u32 s86, s42, 0x80
	s_addc_u32 s87, s43, 0
	s_add_u32 s56, s44, 0x80
	s_addc_u32 s57, s45, 0
	s_add_i32 s35, s41, s83
	s_cmpk_gt_i32 s35, 0x3e7
	s_cselect_b64 s[38:39], -1, 0
	s_cmpk_lt_i32 s35, 0x3e8
	s_cselect_b32 s2, s35, s41
	s_mul_hi_i32 s3, s2, 0x51eb851f
	s_lshr_b32 s37, s3, 31
	s_ashr_i32 s3, s3, 6
	s_add_i32 s3, s3, s37
	s_mul_i32 s37, s3, 0xc8
	s_sub_i32 s2, s2, s37
	s_lshl_b32 s3, s3, 3
	s_add_i32 s3, s3, s40
	s_and_b32 s37, s2, 7
	s_or_b32 s3, s3, s37
	s_lshl_b32 s37, s2, 4
	s_lshl_b32 s2, s3, 8
	s_ashr_i32 s3, s2, 31
	s_and_b32 s42, s37, 0xffffff80
	s_lshl_b64 s[2:3], s[2:3], 11
	s_add_u32 s2, s20, s2
	s_addc_u32 s3, s21, s3
	s_ashr_i32 s43, s42, 31
	s_lshl_b64 s[42:43], s[42:43], 11
	s_add_u32 s42, s0, s42
	s_addc_u32 s43, s1, s43
	s_mov_b64 s[58:59], s[2:3]
	s_mov_b64 s[60:61], s[42:43]
	s_mov_b32 s65, 0
	v_mov_b32_e32 v2, 0
	v_mov_b32_e32 v3, v2
	v_mov_b32_e32 v4, v2
	v_mov_b32_e32 v5, v2
	v_mov_b32_e32 v6, v2
	v_mov_b32_e32 v7, v2
	v_mov_b32_e32 v8, v2
	v_mov_b32_e32 v9, v2
	v_mov_b32_e32 v10, v2
	v_mov_b32_e32 v11, v2
	v_mov_b32_e32 v12, v2
	v_mov_b32_e32 v13, v2
	v_mov_b32_e32 v14, v2
	v_mov_b32_e32 v15, v2
	v_mov_b32_e32 v16, v2
	v_mov_b32_e32 v17, v2
	v_mov_b32_e32 v18, v2
	v_mov_b32_e32 v19, v2
	v_mov_b32_e32 v20, v2
	v_mov_b32_e32 v21, v2
	v_mov_b32_e32 v22, v2
	v_mov_b32_e32 v23, v2
	v_mov_b32_e32 v24, v2
	v_mov_b32_e32 v25, v2
	v_mov_b32_e32 v26, v2
	v_mov_b32_e32 v27, v2
	v_mov_b32_e32 v28, v2
	v_mov_b32_e32 v29, v2
	v_mov_b32_e32 v30, v2
	v_mov_b32_e32 v31, v2
	v_mov_b32_e32 v32, v2
	v_mov_b32_e32 v33, v2
	v_mov_b32_e32 v34, v2
	v_mov_b32_e32 v35, v2
	v_mov_b32_e32 v36, v2
	v_mov_b32_e32 v37, v2
	v_mov_b32_e32 v38, v2
	v_mov_b32_e32 v39, v2
	v_mov_b32_e32 v40, v2
	v_mov_b32_e32 v41, v2
	v_mov_b32_e32 v42, v2
	v_mov_b32_e32 v43, v2
	v_mov_b32_e32 v44, v2
	v_mov_b32_e32 v45, v2
	v_mov_b32_e32 v46, v2
	v_mov_b32_e32 v47, v2
	v_mov_b32_e32 v48, v2
	v_mov_b32_e32 v49, v2
	v_mov_b32_e32 v50, v2
	v_mov_b32_e32 v51, v2
	v_mov_b32_e32 v52, v2
	v_mov_b32_e32 v53, v2
	v_mov_b32_e32 v54, v2
	v_mov_b32_e32 v55, v2
	v_mov_b32_e32 v56, v2
	v_mov_b32_e32 v57, v2
	v_mov_b32_e32 v58, v2
	v_mov_b32_e32 v59, v2
	v_mov_b32_e32 v60, v2
	v_mov_b32_e32 v61, v2
	v_mov_b32_e32 v62, v2
	v_mov_b32_e32 v63, v2
	v_mov_b32_e32 v64, v2
	v_mov_b32_e32 v65, v2
	v_mov_b32_e32 v66, v2
	v_mov_b32_e32 v67, v2
	v_mov_b32_e32 v68, v2
	v_mov_b32_e32 v69, v2
	v_mov_b32_e32 v70, v2
	v_mov_b32_e32 v71, v2
	v_mov_b32_e32 v72, v2
	v_mov_b32_e32 v73, v2
	v_mov_b32_e32 v74, v2
	v_mov_b32_e32 v75, v2
	v_mov_b32_e32 v76, v2
	v_mov_b32_e32 v77, v2
	v_mov_b32_e32 v78, v2
	v_mov_b32_e32 v79, v2
	v_mov_b32_e32 v80, v2
	v_mov_b32_e32 v81, v2
	v_mov_b32_e32 v82, v2
	v_mov_b32_e32 v83, v2
	v_mov_b32_e32 v84, v2
	v_mov_b32_e32 v85, v2
	v_mov_b32_e32 v86, v2
	v_mov_b32_e32 v87, v2
	v_mov_b32_e32 v88, v2
	v_mov_b32_e32 v89, v2
	v_mov_b32_e32 v90, v2
	v_mov_b32_e32 v91, v2
	v_mov_b32_e32 v92, v2
	v_mov_b32_e32 v93, v2
	v_mov_b32_e32 v94, v2
	v_mov_b32_e32 v95, v2
	v_mov_b32_e32 v96, v2
	v_mov_b32_e32 v97, v2
	v_mov_b32_e32 v98, v2
	v_mov_b32_e32 v99, v2
	v_mov_b32_e32 v100, v2
	v_mov_b32_e32 v101, v2
	v_mov_b32_e32 v102, v2
	v_mov_b32_e32 v103, v2
	v_mov_b32_e32 v104, v2
	v_mov_b32_e32 v105, v2
	v_mov_b32_e32 v106, v2
	v_mov_b32_e32 v107, v2
	v_mov_b32_e32 v108, v2
	v_mov_b32_e32 v109, v2
	v_mov_b32_e32 v110, v2
	v_mov_b32_e32 v111, v2
	v_mov_b32_e32 v112, v2
	v_mov_b32_e32 v113, v2
	v_mov_b32_e32 v114, v2
	v_mov_b32_e32 v115, v2
	v_mov_b32_e32 v116, v2
	v_mov_b32_e32 v117, v2
	v_mov_b32_e32 v118, v2
	v_mov_b32_e32 v119, v2
	v_mov_b32_e32 v120, v2
	v_mov_b32_e32 v121, v2
	v_mov_b32_e32 v122, v2
	v_mov_b32_e32 v123, v2
	v_mov_b32_e32 v124, v2
	v_mov_b32_e32 v125, v2
	v_mov_b32_e32 v126, v2
	v_mov_b32_e32 v127, v2
	v_mov_b32_e32 v128, v2
	v_mov_b32_e32 v129, v2

.Lg2_wd:
	s_barrier
	v_add_u32_e32 v130, s50, v212
	v_add_u32_e32 v131, s50, v213
	s_xor_b32 s16, s50, 0x8000
	s_add_u32 m0, s16, s52
	ds_read_b128 v[236:239], v192
	ds_read_b128 v[240:243], v192 offset:2048
	ds_read_b128 v[244:247], v192 offset:4096
	ds_read_b128 v[146:149], v192 offset:6144
	ds_read_b128 v[150:153], v193
	ds_read_b128 v[154:157], v193 offset:2048
	ds_read_b128 v[158:161], v193 offset:4096
	ds_read_b128 v[162:165], v193 offset:6144
	ds_read_b128 v[168:171], v130
	ds_read_b128 v[172:175], v130 offset:2048
	ds_read_b128 v[176:179], v130 offset:4096
	ds_read_b128 v[180:183], v130 offset:6144
	ds_read_b128 v[184:187], v130 offset:8192
	ds_read_b128 v[188:191], v130 offset:10240
	ds_read_b128 v[228:231], v130 offset:12288
	global_load_lds_dwordx4 v200, s[86:87]
	global_load_lds_dwordx4 v201, s[86:87] offset:1024
	global_load_lds_dwordx4 v202, s[86:87] offset:2048
	global_load_lds_dwordx4 v203, s[86:87] offset:3072
	s_add_u32 m0, m0, 0x1000
	s_nop 0
	global_load_lds_dwordx4 v204, s[86:87]
	global_load_lds_dwordx4 v205, s[86:87] offset:1024
	global_load_lds_dwordx4 v206, s[86:87] offset:2048
	global_load_lds_dwordx4 v207, s[86:87] offset:3072
	s_waitcnt lgkmcnt(7)
	s_barrier
; DEVI void lds_barrier() { asm volatile("s_waitcnt lgkmcnt(0)\n\ts_barrier" ::: "memory"); }
; #define SSTORE2(P, buf_) do { \
;     *(uint4*)(wA + (buf_) * 256 * GS2) = P##a0; *(uint4*)(wA + (buf_) * 256 * GS2 + 64 * GS2) = P##a1; \
;     *(uint4*)(wA + (buf_) * 256 * GS2 + 128 * GS2) = P##a2; *(uint4*)(wA + (buf_) * 256 * GS2 + 192 * GS2) = P##a3; \
;     *(uint4*)(wB + (buf_) * 128 * GS2) = P##b0; *(uint4*)(wB + (buf_) * 128 * GS2 + 64 * GS2) = P##b1; } while (0)
; DEVI void gemm_kloop2(const bf16_t* __restrict__ A, size_t lda, const bf16_t* __restrict__ Bt, size_t ldb,
;                       const bf16_t* __restrict__ nA, size_t nlda, const bf16_t* __restrict__ nBt, size_t nldb,
;                       bool first, bf16_t* smem, f32x4 (&acc)[8][4]) {
;     ...
; #pragma unroll 1
;   for (int kt = 0; kt < nk - 2; kt += 2) {
;     COMPUTE2(0, GLOAD2(x, gA, gB, lda, ldb, kt + 1));
;     SSTORE2(x, 1);
;     lds_barrier();
;     COMPUTE2(1, GLOAD2(x, gA, gB, lda, ldb, kt + 2));
;     SSTORE2(x, 0);
;     lds_barrier();
;   }
	s_mov_b32 m0, s53
	s_nop 0
	global_load_lds_dwordx4 v208, s[56:57]
	global_load_lds_dwordx4 v209, s[56:57] offset:1024
	global_load_lds_dwordx4 v210, s[56:57] offset:2048
	global_load_lds_dwordx4 v211, s[56:57] offset:3072
	ds_read_b128 v[232:235], v130 offset:14336
	s_setprio 1
	s_waitcnt lgkmcnt(7)
	v_mfma_f32_16x16x32_bf16 v[114:117], v[236:239], v[168:171], v[114:117]
	v_mfma_f32_16x16x32_bf16 v[102:105], v[240:243], v[168:171], v[102:105]
	v_mfma_f32_16x16x32_bf16 v[94:97], v[244:247], v[168:171], v[94:97]
	v_mfma_f32_16x16x32_bf16 v[86:89], v[146:149], v[168:171], v[86:89]
	s_waitcnt lgkmcnt(6)
	v_mfma_f32_16x16x32_bf16 v[126:129], v[236:239], v[172:175], v[126:129]
	v_mfma_f32_16x16x32_bf16 v[122:125], v[240:243], v[172:175], v[122:125]
	ds_read_b128 v[168:171], v131
	v_mfma_f32_16x16x32_bf16 v[118:121], v[244:247], v[172:175], v[118:121]
	v_mfma_f32_16x16x32_bf16 v[110:113], v[146:149], v[172:175], v[110:113]
	s_waitcnt lgkmcnt(6)
	v_mfma_f32_16x16x32_bf16 v[106:109], v[236:239], v[176:179], v[106:109]
	v_mfma_f32_16x16x32_bf16 v[98:101], v[240:243], v[176:179], v[98:101]
	ds_read_b128 v[172:175], v131 offset:2048
	v_mfma_f32_16x16x32_bf16 v[90:93], v[244:247], v[176:179], v[90:93]
	v_mfma_f32_16x16x32_bf16 v[82:85], v[146:149], v[176:179], v[82:85]
	s_waitcnt lgkmcnt(6)
	v_mfma_f32_16x16x32_bf16 v[78:81], v[236:239], v[180:183], v[78:81]
	v_mfma_f32_16x16x32_bf16 v[74:77], v[240:243], v[180:183], v[74:77]
	ds_read_b128 v[176:179], v131 offset:4096
	v_mfma_f32_16x16x32_bf16 v[70:73], v[244:247], v[180:183], v[70:73]
	v_mfma_f32_16x16x32_bf16 v[66:69], v[146:149], v[180:183], v[66:69]
	s_waitcnt lgkmcnt(6)
	v_mfma_f32_16x16x32_bf16 v[62:65], v[236:239], v[184:187], v[62:65]
	v_mfma_f32_16x16x32_bf16 v[58:61], v[240:243], v[184:187], v[58:61]
	ds_read_b128 v[180:183], v131 offset:6144
	v_mfma_f32_16x16x32_bf16 v[54:57], v[244:247], v[184:187], v[54:57]
	v_mfma_f32_16x16x32_bf16 v[50:53], v[146:149], v[184:187], v[50:53]
	s_waitcnt lgkmcnt(6)
	v_mfma_f32_16x16x32_bf16 v[46:49], v[236:239], v[188:191], v[46:49]
	v_mfma_f32_16x16x32_bf16 v[42:45], v[240:243], v[188:191], v[42:45]
	ds_read_b128 v[184:187], v131 offset:8192
	v_mfma_f32_16x16x32_bf16 v[38:41], v[244:247], v[188:191], v[38:41]
	v_mfma_f32_16x16x32_bf16 v[34:37], v[146:149], v[188:191], v[34:37]
	s_waitcnt lgkmcnt(6)
	v_mfma_f32_16x16x32_bf16 v[30:33], v[236:239], v[228:231], v[30:33]
	v_mfma_f32_16x16x32_bf16 v[26:29], v[240:243], v[228:231], v[26:29]
	ds_read_b128 v[188:191], v131 offset:10240
	v_mfma_f32_16x16x32_bf16 v[22:25], v[244:247], v[228:231], v[22:25]
	v_mfma_f32_16x16x32_bf16 v[18:21], v[146:149], v[228:231], v[18:21]
	s_waitcnt lgkmcnt(6)
	v_mfma_f32_16x16x32_bf16 v[14:17], v[236:239], v[232:235], v[14:17]
	v_mfma_f32_16x16x32_bf16 v[10:13], v[240:243], v[232:235], v[10:13]
	ds_read_b128 v[228:231], v131 offset:12288
	v_mfma_f32_16x16x32_bf16 v[6:9], v[244:247], v[232:235], v[6:9]
	v_mfma_f32_16x16x32_bf16 v[2:5], v[146:149], v[232:235], v[2:5]
	s_waitcnt lgkmcnt(6)
	v_mfma_f32_16x16x32_bf16 v[114:117], v[150:153], v[168:171], v[114:117]
	v_mfma_f32_16x16x32_bf16 v[102:105], v[154:157], v[168:171], v[102:105]
	ds_read_b128 v[232:235], v131 offset:14336
	v_mfma_f32_16x16x32_bf16 v[94:97], v[158:161], v[168:171], v[94:97]
	v_mfma_f32_16x16x32_bf16 v[86:89], v[162:165], v[168:171], v[86:89]
	s_add_u32 s86, s86, 0x80
	s_waitcnt lgkmcnt(6)
	v_mfma_f32_16x16x32_bf16 v[126:129], v[150:153], v[172:175], v[126:129]
	v_mfma_f32_16x16x32_bf16 v[122:125], v[154:157], v[172:175], v[122:125]
	v_mfma_f32_16x16x32_bf16 v[118:121], v[158:161], v[172:175], v[118:121]
	v_mfma_f32_16x16x32_bf16 v[110:113], v[162:165], v[172:175], v[110:113]
	s_addc_u32 s87, s87, 0
	s_waitcnt lgkmcnt(5)
	v_mfma_f32_16x16x32_bf16 v[106:109], v[150:153], v[176:179], v[106:109]
	v_mfma_f32_16x16x32_bf16 v[98:101], v[154:157], v[176:179], v[98:101]
	v_mfma_f32_16x16x32_bf16 v[90:93], v[158:161], v[176:179], v[90:93]
	v_mfma_f32_16x16x32_bf16 v[82:85], v[162:165], v[176:179], v[82:85]
	s_add_u32 s56, s56, 0x80
	s_waitcnt lgkmcnt(4)
	v_mfma_f32_16x16x32_bf16 v[78:81], v[150:153], v[180:183], v[78:81]
	v_mfma_f32_16x16x32_bf16 v[74:77], v[154:157], v[180:183], v[74:77]
	v_mfma_f32_16x16x32_bf16 v[70:73], v[158:161], v[180:183], v[70:73]
	v_mfma_f32_16x16x32_bf16 v[66:69], v[162:165], v[180:183], v[66:69]
	s_addc_u32 s57, s57, 0
	s_waitcnt lgkmcnt(3)
	v_mfma_f32_16x16x32_bf16 v[62:65], v[150:153], v[184:187], v[62:65]
	v_mfma_f32_16x16x32_bf16 v[58:61], v[154:157], v[184:187], v[58:61]
	v_mfma_f32_16x16x32_bf16 v[54:57], v[158:161], v[184:187], v[54:57]
	v_mfma_f32_16x16x32_bf16 v[50:53], v[162:165], v[184:187], v[50:53]
	s_xor_b32 s50, s50, 0x8000
	s_waitcnt lgkmcnt(2)
	v_mfma_f32_16x16x32_bf16 v[46:49], v[150:153], v[188:191], v[46:49]
	v_mfma_f32_16x16x32_bf16 v[42:45], v[154:157], v[188:191], v[42:45]
	v_mfma_f32_16x16x32_bf16 v[38:41], v[158:161], v[188:191], v[38:41]
	v_mfma_f32_16x16x32_bf16 v[34:37], v[162:165], v[188:191], v[34:37]
	s_add_u32 s65, s65, 1
	s_waitcnt lgkmcnt(1)
	v_mfma_f32_16x16x32_bf16 v[30:33], v[150:153], v[228:231], v[30:33]
	v_mfma_f32_16x16x32_bf16 v[26:29], v[154:157], v[228:231], v[26:29]
	v_mfma_f32_16x16x32_bf16 v[22:25], v[158:161], v[228:231], v[22:25]
	v_mfma_f32_16x16x32_bf16 v[18:21], v[162:165], v[228:231], v[18:21]
	s_cmp_eq_u32 s65, 15
	s_waitcnt lgkmcnt(0)
	v_mfma_f32_16x16x32_bf16 v[14:17], v[150:153], v[232:235], v[14:17]
	v_mfma_f32_16x16x32_bf16 v[10:13], v[154:157], v[232:235], v[10:13]
	v_mfma_f32_16x16x32_bf16 v[6:9], v[158:161], v[232:235], v[6:9]
	v_mfma_f32_16x16x32_bf16 v[2:5], v[162:165], v[232:235], v[2:5]
	s_cselect_b64 s[86:87], s[58:59], s[86:87]
	s_cselect_b64 s[56:57], s[60:61], s[56:57]
	s_setprio 0
	s_cmp_lt_u32 s65, 16
	s_cbranch_scc1 .Lg2_loop
	s_nop 7
	s_nop 3
	v_add_u32_e32 v130, s36, v142
	s_cmpk_gt_i32 s34, 0x87f
	v_ashrrev_i32_e32 v131, 31, v130
	s_mov_b64 s[2:3], -1
	s_cbranch_scc1 .LBB0_633
	s_andn2_b64 vcc, exec, s[2:3]
	s_cbranch_vccnz .LBB0_626
	s_branch .LBB0_634

; DEVI void phase_gemm_big(const Params& p, int mode, bf16_t* smem) {
;     ...
;   for (int L = li; L < per_xcd; L += nli) {
;     const int mg = L / (8 * NT), rem = L % (8 * NT), nt = rem >> 3, mt = xcd * 40 + mg * 8 + (rem & 7), m0 = mt * 256, n0 = nt * 128;
;     const int Ln = L + nli < per_xcd ? L + nli : L;
;     const int mgn = Ln / (8 * NT), remn = Ln % (8 * NT), m0n = (xcd * 40 + mgn * 8 + (remn & 7)) * 256, n0n = (remn >> 3) * 128;
;     f32x4 acc[8][4];
; #pragma unroll
;     for (int i = 0; i < 8; ++i)
; #pragma unroll
;       for (int j = 0; j < 4; ++j) acc[i][j] = (f32x4){0.f, 0.f, 0.f, 0.f};
;     gemm_kloop2(Abase + (size_t)m0 * 1024, 1024, Bbase + (size_t)n0 * 1024, 1024,
;                 Abase + (size_t)m0n * 1024, 1024, Bbase + (size_t)n0n * 1024, 1024, first, smem, acc);
.Lg3_go:
	s_add_u32 s86, s42, 0x80
	s_addc_u32 s87, s43, 0
	s_add_u32 s56, s44, 0x80
	s_addc_u32 s57, s45, 0
	s_add_i32 s35, s41, s83
	s_cmpk_gt_i32 s35, 0x4ff
	s_cselect_b64 s[38:39], -1, 0
	s_cmpk_lt_i32 s35, 0x500
	s_cselect_b32 s2, s35, s41
	s_ashr_i32 s3, s2, 31
	s_lshr_b32 s3, s3, 24
	s_add_i32 s3, s2, s3
	s_and_b32 s37, s3, 0xffffff00
	s_lshr_b32 s3, s3, 5
	s_sub_i32 s2, s2, s37
	s_and_b32 s3, s3, 0x7fffff8
	s_add_i32 s3, s3, s40
	s_and_b32 s37, s2, 7
	s_or_b32 s3, s3, s37
	s_lshl_b32 s37, s2, 4
	s_lshl_b32 s2, s3, 8
	s_ashr_i32 s3, s2, 31
	s_and_b32 s42, s37, 0xffffff80
	s_lshl_b64 s[2:3], s[2:3], 11
	s_add_u32 s2, s20, s2
	s_addc_u32 s3, s21, s3
	s_ashr_i32 s43, s42, 31
	s_lshl_b64 s[42:43], s[42:43], 11
	s_add_u32 s42, s0, s42
	s_addc_u32 s43, s1, s43
	s_mov_b64 s[58:59], s[2:3]
	s_mov_b64 s[60:61], s[42:43]
	s_mov_b32 s65, 0
	v_mov_b32_e32 v2, 0
	v_mov_b32_e32 v3, v2
	v_mov_b32_e32 v4, v2
	v_mov_b32_e32 v5, v2
	v_mov_b32_e32 v6, v2
	v_mov_b32_e32 v7, v2
	v_mov_b32_e32 v8, v2
	v_mov_b32_e32 v9, v2
	v_mov_b32_e32 v10, v2
	v_mov_b32_e32 v11, v2
	v_mov_b32_e32 v12, v2
	v_mov_b32_e32 v13, v2
	v_mov_b32_e32 v14, v2
	v_mov_b32_e32 v15, v2
	v_mov_b32_e32 v16, v2
	v_mov_b32_e32 v17, v2
	v_mov_b32_e32 v18, v2
	v_mov_b32_e32 v19, v2
	v_mov_b32_e32 v20, v2
	v_mov_b32_e32 v21, v2
	v_mov_b32_e32 v22, v2
	v_mov_b32_e32 v23, v2
	v_mov_b32_e32 v24, v2
	v_mov_b32_e32 v25, v2
	v_mov_b32_e32 v26, v2
	v_mov_b32_e32 v27, v2
	v_mov_b32_e32 v28, v2
	v_mov_b32_e32 v29, v2
	v_mov_b32_e32 v30, v2
	v_mov_b32_e32 v31, v2
	v_mov_b32_e32 v32, v2
	v_mov_b32_e32 v33, v2
	v_mov_b32_e32 v34, v2
	v_mov_b32_e32 v35, v2
	v_mov_b32_e32 v36, v2
	v_mov_b32_e32 v37, v2
	v_mov_b32_e32 v38, v2
	v_mov_b32_e32 v39, v2
	v_mov_b32_e32 v40, v2
	v_mov_b32_e32 v41, v2
	v_mov_b32_e32 v42, v2
	v_mov_b32_e32 v43, v2
	v_mov_b32_e32 v44, v2
	v_mov_b32_e32 v45, v2
	v_mov_b32_e32 v46, v2
	v_mov_b32_e32 v47, v2
	v_mov_b32_e32 v48, v2
	v_mov_b32_e32 v49, v2
	v_mov_b32_e32 v50, v2
	v_mov_b32_e32 v51, v2
	v_mov_b32_e32 v52, v2
	v_mov_b32_e32 v53, v2
	v_mov_b32_e32 v54, v2
	v_mov_b32_e32 v55, v2
	v_mov_b32_e32 v56, v2
	v_mov_b32_e32 v57, v2
	v_mov_b32_e32 v58, v2
	v_mov_b32_e32 v59, v2
	v_mov_b32_e32 v60, v2
	v_mov_b32_e32 v61, v2
	v_mov_b32_e32 v62, v2
	v_mov_b32_e32 v63, v2
	v_mov_b32_e32 v64, v2
	v_mov_b32_e32 v65, v2
	v_mov_b32_e32 v66, v2
	v_mov_b32_e32 v67, v2
	v_mov_b32_e32 v68, v2
	v_mov_b32_e32 v69, v2
	v_mov_b32_e32 v70, v2
	v_mov_b32_e32 v71, v2
	v_mov_b32_e32 v72, v2
	v_mov_b32_e32 v73, v2
	v_mov_b32_e32 v74, v2
	v_mov_b32_e32 v75, v2
	v_mov_b32_e32 v76, v2
	v_mov_b32_e32 v77, v2
	v_mov_b32_e32 v78, v2
	v_mov_b32_e32 v79, v2
	v_mov_b32_e32 v80, v2
	v_mov_b32_e32 v81, v2
	v_mov_b32_e32 v82, v2
	v_mov_b32_e32 v83, v2
	v_mov_b32_e32 v84, v2
	v_mov_b32_e32 v85, v2
	v_mov_b32_e32 v86, v2
	v_mov_b32_e32 v87, v2
	v_mov_b32_e32 v88, v2
	v_mov_b32_e32 v89, v2
	v_mov_b32_e32 v90, v2
	v_mov_b32_e32 v91, v2
	v_mov_b32_e32 v92, v2
	v_mov_b32_e32 v93, v2
	v_mov_b32_e32 v94, v2
	v_mov_b32_e32 v95, v2
	v_mov_b32_e32 v96, v2
	v_mov_b32_e32 v97, v2
	v_mov_b32_e32 v98, v2
	v_mov_b32_e32 v99, v2
	v_mov_b32_e32 v100, v2
	v_mov_b32_e32 v101, v2
	v_mov_b32_e32 v102, v2
	v_mov_b32_e32 v103, v2
	v_mov_b32_e32 v104, v2
	v_mov_b32_e32 v105, v2
	v_mov_b32_e32 v106, v2
	v_mov_b32_e32 v107, v2
	v_mov_b32_e32 v108, v2
	v_mov_b32_e32 v109, v2
	v_mov_b32_e32 v110, v2
	v_mov_b32_e32 v111, v2
	v_mov_b32_e32 v112, v2
	v_mov_b32_e32 v113, v2
	v_mov_b32_e32 v114, v2
	v_mov_b32_e32 v115, v2
	v_mov_b32_e32 v116, v2
	v_mov_b32_e32 v117, v2
	v_mov_b32_e32 v118, v2
	v_mov_b32_e32 v119, v2
	v_mov_b32_e32 v120, v2
	v_mov_b32_e32 v121, v2
	v_mov_b32_e32 v122, v2
	v_mov_b32_e32 v123, v2
	v_mov_b32_e32 v124, v2
	v_mov_b32_e32 v125, v2
	v_mov_b32_e32 v126, v2
	v_mov_b32_e32 v127, v2
	v_mov_b32_e32 v128, v2
	v_mov_b32_e32 v129, v2

.Lg3_wd:
	s_barrier
	v_add_u32_e32 v130, s50, v212
	v_add_u32_e32 v131, s50, v213
	s_xor_b32 s16, s50, 0x8000
	s_add_u32 m0, s16, s52
	ds_read_b128 v[236:239], v192
	ds_read_b128 v[240:243], v192 offset:2048
	ds_read_b128 v[244:247], v192 offset:4096
	ds_read_b128 v[146:149], v192 offset:6144
	ds_read_b128 v[150:153], v193
	ds_read_b128 v[154:157], v193 offset:2048
	ds_read_b128 v[158:161], v193 offset:4096
	ds_read_b128 v[162:165], v193 offset:6144
	ds_read_b128 v[168:171], v130
	ds_read_b128 v[172:175], v130 offset:2048
	ds_read_b128 v[176:179], v130 offset:4096
	ds_read_b128 v[180:183], v130 offset:6144
	ds_read_b128 v[184:187], v130 offset:8192
	ds_read_b128 v[188:191], v130 offset:10240
	ds_read_b128 v[228:231], v130 offset:12288
	global_load_lds_dwordx4 v200, s[86:87]
	global_load_lds_dwordx4 v201, s[86:87] offset:1024
	global_load_lds_dwordx4 v202, s[86:87] offset:2048
	global_load_lds_dwordx4 v203, s[86:87] offset:3072
	s_add_u32 m0, m0, 0x1000
	s_nop 0
	global_load_lds_dwordx4 v204, s[86:87]
	global_load_lds_dwordx4 v205, s[86:87] offset:1024
	global_load_lds_dwordx4 v206, s[86:87] offset:2048
	global_load_lds_dwordx4 v207, s[86:87] offset:3072
	s_waitcnt lgkmcnt(7)
	s_barrier
; DEVI void lds_barrier() { asm volatile("s_waitcnt lgkmcnt(0)\n\ts_barrier" ::: "memory"); }
; #define SSTORE2(P, buf_) do { \
;     *(uint4*)(wA + (buf_) * 256 * GS2) = P##a0; *(uint4*)(wA + (buf_) * 256 * GS2 + 64 * GS2) = P##a1; \
;     *(uint4*)(wA + (buf_) * 256 * GS2 + 128 * GS2) = P##a2; *(uint4*)(wA + (buf_) * 256 * GS2 + 192 * GS2) = P##a3; \
;     *(uint4*)(wB + (buf_) * 128 * GS2) = P##b0; *(uint4*)(wB + (buf_) * 128 * GS2 + 64 * GS2) = P##b1; } while (0)
; DEVI void gemm_kloop2(const bf16_t* __restrict__ A, size_t lda, const bf16_t* __restrict__ Bt, size_t ldb,
;                       const bf16_t* __restrict__ nA, size_t nlda, const bf16_t* __restrict__ nBt, size_t nldb,
;                       bool first, bf16_t* smem, f32x4 (&acc)[8][4]) {
;     ...
; #pragma unroll 1
;   for (int kt = 0; kt < nk - 2; kt += 2) {
;     COMPUTE2(0, GLOAD2(x, gA, gB, lda, ldb, kt + 1));
;     SSTORE2(x, 1);
;     lds_barrier();
;     COMPUTE2(1, GLOAD2(x, gA, gB, lda, ldb, kt + 2));
;     SSTORE2(x, 0);
;     lds_barrier();
;   }
	s_mov_b32 m0, s53
	s_nop 0
	global_load_lds_dwordx4 v208, s[56:57]
	global_load_lds_dwordx4 v209, s[56:57] offset:1024
	global_load_lds_dwordx4 v210, s[56:57] offset:2048
	global_load_lds_dwordx4 v211, s[56:57] offset:3072
	ds_read_b128 v[232:235], v130 offset:14336
	s_setprio 1
	s_waitcnt lgkmcnt(7)
	v_mfma_f32_16x16x32_bf16 v[114:117], v[236:239], v[168:171], v[114:117]
	v_mfma_f32_16x16x32_bf16 v[102:105], v[240:243], v[168:171], v[102:105]
	v_mfma_f32_16x16x32_bf16 v[94:97], v[244:247], v[168:171], v[94:97]
	v_mfma_f32_16x16x32_bf16 v[86:89], v[146:149], v[168:171], v[86:89]
	s_waitcnt lgkmcnt(6)
	v_mfma_f32_16x16x32_bf16 v[126:129], v[236:239], v[172:175], v[126:129]
	v_mfma_f32_16x16x32_bf16 v[122:125], v[240:243], v[172:175], v[122:125]
	ds_read_b128 v[168:171], v131
	v_mfma_f32_16x16x32_bf16 v[118:121], v[244:247], v[172:175], v[118:121]
	v_mfma_f32_16x16x32_bf16 v[110:113], v[146:149], v[172:175], v[110:113]
	s_waitcnt lgkmcnt(6)
	v_mfma_f32_16x16x32_bf16 v[106:109], v[236:239], v[176:179], v[106:109]
	v_mfma_f32_16x16x32_bf16 v[98:101], v[240:243], v[176:179], v[98:101]
	ds_read_b128 v[172:175], v131 offset:2048
	v_mfma_f32_16x16x32_bf16 v[90:93], v[244:247], v[176:179], v[90:93]
	v_mfma_f32_16x16x32_bf16 v[82:85], v[146:149], v[176:179], v[82:85]
	s_waitcnt lgkmcnt(6)
	v_mfma_f32_16x16x32_bf16 v[78:81], v[236:239], v[180:183], v[78:81]
	v_mfma_f32_16x16x32_bf16 v[74:77], v[240:243], v[180:183], v[74:77]
	ds_read_b128 v[176:179], v131 offset:4096
	v_mfma_f32_16x16x32_bf16 v[70:73], v[244:247], v[180:183], v[70:73]
	v_mfma_f32_16x16x32_bf16 v[66:69], v[146:149], v[180:183], v[66:69]
	s_waitcnt lgkmcnt(6)
	v_mfma_f32_16x16x32_bf16 v[62:65], v[236:239], v[184:187], v[62:65]
	v_mfma_f32_16x16x32_bf16 v[58:61], v[240:243], v[184:187], v[58:61]
	ds_read_b128 v[180:183], v131 offset:6144
	v_mfma_f32_16x16x32_bf16 v[54:57], v[244:247], v[184:187], v[54:57]
	v_mfma_f32_16x16x32_bf16 v[50:53], v[146:149], v[184:187], v[50:53]
	s_waitcnt lgkmcnt(6)
	v_mfma_f32_16x16x32_bf16 v[46:49], v[236:239], v[188:191], v[46:49]
	v_mfma_f32_16x16x32_bf16 v[42:45], v[240:243], v[188:191], v[42:45]
	ds_read_b128 v[184:187], v131 offset:8192
	v_mfma_f32_16x16x32_bf16 v[38:41], v[244:247], v[188:191], v[38:41]
	v_mfma_f32_16x16x32_bf16 v[34:37], v[146:149], v[188:191], v[34:37]
	s_waitcnt lgkmcnt(6)
	v_mfma_f32_16x16x32_bf16 v[30:33], v[236:239], v[228:231], v[30:33]
	v_mfma_f32_16x16x32_bf16 v[26:29], v[240:243], v[228:231], v[26:29]
	ds_read_b128 v[188:191], v131 offset:10240
	v_mfma_f32_16x16x32_bf16 v[22:25], v[244:247], v[228:231], v[22:25]
	v_mfma_f32_16x16x32_bf16 v[18:21], v[146:149], v[228:231], v[18:21]
	s_waitcnt lgkmcnt(6)
	v_mfma_f32_16x16x32_bf16 v[14:17], v[236:239], v[232:235], v[14:17]
	v_mfma_f32_16x16x32_bf16 v[10:13], v[240:243], v[232:235], v[10:13]
	ds_read_b128 v[228:231], v131 offset:12288
	v_mfma_f32_16x16x32_bf16 v[6:9], v[244:247], v[232:235], v[6:9]
	v_mfma_f32_16x16x32_bf16 v[2:5], v[146:149], v[232:235], v[2:5]
	s_waitcnt lgkmcnt(6)
	v_mfma_f32_16x16x32_bf16 v[114:117], v[150:153], v[168:171], v[114:117]
	v_mfma_f32_16x16x32_bf16 v[102:105], v[154:157], v[168:171], v[102:105]
	ds_read_b128 v[232:235], v131 offset:14336
	v_mfma_f32_16x16x32_bf16 v[94:97], v[158:161], v[168:171], v[94:97]
	v_mfma_f32_16x16x32_bf16 v[86:89], v[162:165], v[168:171], v[86:89]
	s_add_u32 s86, s86, 0x80
	s_waitcnt lgkmcnt(6)
	v_mfma_f32_16x16x32_bf16 v[126:129], v[150:153], v[172:175], v[126:129]
	v_mfma_f32_16x16x32_bf16 v[122:125], v[154:157], v[172:175], v[122:125]
	v_mfma_f32_16x16x32_bf16 v[118:121], v[158:161], v[172:175], v[118:121]
	v_mfma_f32_16x16x32_bf16 v[110:113], v[162:165], v[172:175], v[110:113]
	s_addc_u32 s87, s87, 0
	s_waitcnt lgkmcnt(5)
	v_mfma_f32_16x16x32_bf16 v[106:109], v[150:153], v[176:179], v[106:109]
	v_mfma_f32_16x16x32_bf16 v[98:101], v[154:157], v[176:179], v[98:101]
	v_mfma_f32_16x16x32_bf16 v[90:93], v[158:161], v[176:179], v[90:93]
	v_mfma_f32_16x16x32_bf16 v[82:85], v[162:165], v[176:179], v[82:85]
	s_add_u32 s56, s56, 0x80
	s_waitcnt lgkmcnt(4)
	v_mfma_f32_16x16x32_bf16 v[78:81], v[150:153], v[180:183], v[78:81]
	v_mfma_f32_16x16x32_bf16 v[74:77], v[154:157], v[180:183], v[74:77]
	v_mfma_f32_16x16x32_bf16 v[70:73], v[158:161], v[180:183], v[70:73]
	v_mfma_f32_16x16x32_bf16 v[66:69], v[162:165], v[180:183], v[66:69]
	s_addc_u32 s57, s57, 0
	s_waitcnt lgkmcnt(3)
	v_mfma_f32_16x16x32_bf16 v[62:65], v[150:153], v[184:187], v[62:65]
	v_mfma_f32_16x16x32_bf16 v[58:61], v[154:157], v[184:187], v[58:61]
	v_mfma_f32_16x16x32_bf16 v[54:57], v[158:161], v[184:187], v[54:57]
	v_mfma_f32_16x16x32_bf16 v[50:53], v[162:165], v[184:187], v[50:53]
	s_xor_b32 s50, s50, 0x8000
	s_waitcnt lgkmcnt(2)
	v_mfma_f32_16x16x32_bf16 v[46:49], v[150:153], v[188:191], v[46:49]
	v_mfma_f32_16x16x32_bf16 v[42:45], v[154:157], v[188:191], v[42:45]
	v_mfma_f32_16x16x32_bf16 v[38:41], v[158:161], v[188:191], v[38:41]
	v_mfma_f32_16x16x32_bf16 v[34:37], v[162:165], v[188:191], v[34:37]
	s_add_u32 s65, s65, 1
	s_waitcnt lgkmcnt(1)
	v_mfma_f32_16x16x32_bf16 v[30:33], v[150:153], v[228:231], v[30:33]
	v_mfma_f32_16x16x32_bf16 v[26:29], v[154:157], v[228:231], v[26:29]
	v_mfma_f32_16x16x32_bf16 v[22:25], v[158:161], v[228:231], v[22:25]
	v_mfma_f32_16x16x32_bf16 v[18:21], v[162:165], v[228:231], v[18:21]
	s_cmp_eq_u32 s65, 15
	s_waitcnt lgkmcnt(0)
	v_mfma_f32_16x16x32_bf16 v[14:17], v[150:153], v[232:235], v[14:17]
	v_mfma_f32_16x16x32_bf16 v[10:13], v[154:157], v[232:235], v[10:13]
	v_mfma_f32_16x16x32_bf16 v[6:9], v[158:161], v[232:235], v[6:9]
	v_mfma_f32_16x16x32_bf16 v[2:5], v[162:165], v[232:235], v[2:5]
	s_cselect_b64 s[86:87], s[58:59], s[86:87]
	s_cselect_b64 s[56:57], s[60:61], s[56:57]
	s_setprio 0
	s_cmp_lt_u32 s65, 16
	s_cbranch_scc1 .Lg3_loop
	s_nop 7
	s_nop 3
	v_add_u32_e32 v130, s36, v142
	s_cmpk_gt_i32 s34, 0xbff
	v_ashrrev_i32_e32 v131, 31, v130
	s_mov_b64 s[2:3], -1
	s_cbranch_scc1 .LBB0_1119
	s_andn2_b64 vcc, exec, s[2:3]
	s_cbranch_vccnz .LBB0_1112
	s_branch .LBB0_1120
